# mLSTM chunk loop hand-scheduled: all LDS reads issued early in consumption order with counted waits, 4 redundant transpose reads per chunk dropped
# speedup vs baseline: 1.0045x; 1.0045x over previous
.LBB0_252:
	s_and_b32 s0, s4, 1
	s_mul_i32 s23, s0, 0x2400
	s_mul_i32 s1, s0, 0x1b00
	s_mul_i32 s22, s0, 0x1c00
	s_mul_i32 s30, s0, 0x500
	s_xor_b32 s21, s0, 1
	s_add_i32 s1, s16, s1
	s_mul_i32 s34, s21, 0x1b00
	v_add_u32_e32 v168, s23, v109
	v_add_u32_e32 v169, s23, v148
	s_add_i32 s34, s16, s34
	ds_read_b128 v[40:43], v168
	ds_read_b128 v[44:47], v168 offset:64
	ds_read_b128 v[48:51], v169 offset:18432
	ds_read_b128 v[52:55], v169 offset:18496
	ds_read_b128 v[180:183], v169 offset:20736
	ds_read_b128 v[184:187], v169 offset:20800
	ds_read_b128 v[188:191], v169 offset:23040
	ds_read_b128 v[192:195], v169 offset:23104
	ds_read_b128 v[36:39], v169 offset:25344
	ds_read_b128 v[196:199], v169 offset:25408
	v_add3_u32 v179, s1, v110, v108
	v_add3_u32 v208, s1, v111, v108
	ds_read_b128 v[230:233], v179
	ds_read_b128 v[234:237], v179 offset:64
	ds_read_b128 v[238:241], v208 offset:4608
	ds_read_b128 v[242:245], v208 offset:4672
	v_add_u32_e32 v209, s22, v116
	v_add_u32_e32 v0, s30, v107
	v_add_u32_e32 v220, s27, v209
	v_mov_b32_e32 v250, s20
	s_mov_b64 s[92:93], 0
	s_waitcnt lgkmcnt(11)
	v_mfma_f32_16x16x32_bf16 v[48:51], v[48:51], v[40:43], 0
	ds_read_b64_tr_b16 v[200:201], v220
	s_waitcnt lgkmcnt(11)
	v_mfma_f32_16x16x32_bf16 v[48:51], v[52:55], v[44:47], v[48:51]
	ds_read_b64_tr_b16 v[202:203], v220 offset:1792
	s_waitcnt lgkmcnt(11)
	v_mfma_f32_16x16x32_bf16 v[180:183], v[180:183], v[40:43], 0
	ds_read_b64_tr_b16 v[204:205], v209 offset:64
	s_waitcnt lgkmcnt(11)
	v_mfma_f32_16x16x32_bf16 v[180:183], v[184:187], v[44:47], v[180:183]
	ds_read_b64_tr_b16 v[206:207], v209 offset:1856
	s_waitcnt lgkmcnt(11)
	v_mfma_f32_16x16x32_bf16 v[188:191], v[188:191], v[40:43], 0
	ds_read_b64_tr_b16 v[246:247], v220 offset:3584
	s_waitcnt lgkmcnt(11)
	v_mfma_f32_16x16x32_bf16 v[188:191], v[192:195], v[44:47], v[188:191]
	ds_read_b64_tr_b16 v[248:249], v220 offset:5376
	s_waitcnt lgkmcnt(11)
	v_mfma_f32_16x16x32_bf16 v[36:39], v[36:39], v[40:43], 0
	ds_read_b64_tr_b16 v[216:217], v209 offset:3648
	s_waitcnt lgkmcnt(11)
	v_mfma_f32_16x16x32_bf16 v[36:39], v[196:199], v[44:47], v[36:39]
	ds_read_b64_tr_b16 v[218:219], v209 offset:5440
	s_waitcnt lgkmcnt(11)
	v_mfma_f32_16x16x32_bf16 v[230:233], v[230:233], v[40:43], 0
	ds_read2st64_b32 v[2:3], v0 offset0:200 offset1:201
	s_waitcnt lgkmcnt(11)
	v_mfma_f32_16x16x32_bf16 v[230:233], v[234:237], v[44:47], v[230:233]
	ds_read_b32 v0, v0 offset:51712
	s_waitcnt lgkmcnt(11)
	v_mfma_f32_16x16x32_bf16 v[238:241], v[238:241], v[40:43], 0
	ds_read_b32 v176, v250
	s_waitcnt lgkmcnt(11)
	v_mfma_f32_16x16x32_bf16 v[238:241], v[242:245], v[44:47], v[238:241]
	v_add_u32_e32 v168, s23, v113
	v_add_u32_e32 v169, s22, v114
	v_add_u32_e32 v221, s27, v169
	ds_read_b64_tr_b16 v[52:53], v168
	ds_read_b64_tr_b16 v[54:55], v168 offset:2304
	ds_read_b64_tr_b16 v[192:193], v221
	ds_read_b64_tr_b16 v[194:195], v221 offset:1792
	ds_read_b64_tr_b16 v[196:197], v169 offset:64
	ds_read_b64_tr_b16 v[198:199], v169 offset:1856
	ds_read_b64_tr_b16 v[184:185], v168 offset:4608
	ds_read_b64_tr_b16 v[186:187], v168 offset:6912
	ds_read_b64_tr_b16 v[234:235], v221 offset:3584
	ds_read_b64_tr_b16 v[236:237], v221 offset:5376
	ds_read_b64_tr_b16 v[242:243], v169 offset:3648
	ds_read_b64_tr_b16 v[244:245], v169 offset:5440
	v_cndmask_b32_e64 v48, v48, 0, s[60:61]
	v_cndmask_b32_e64 v49, 0, v49, s[62:63]
	v_cndmask_b32_e64 v50, v50, 0, s[64:65]
	v_cndmask_b32_e64 v51, v51, 0, s[90:91]
	v_cndmask_b32_e64 v180, v180, 0, s[66:67]
	v_cndmask_b32_e64 v181, v181, 0, s[68:69]
	v_cndmask_b32_e64 v182, v182, 0, s[70:71]
	v_cndmask_b32_e64 v183, v183, 0, s[72:73]
	v_cndmask_b32_e64 v188, v188, 0, s[74:75]
	v_cndmask_b32_e64 v189, v189, 0, s[76:77]
	v_cndmask_b32_e64 v190, v190, 0, s[78:79]
	v_cndmask_b32_e64 v191, v191, 0, s[80:81]
	v_cndmask_b32_e64 v36, v36, 0, s[82:83]
	v_cndmask_b32_e64 v37, v37, 0, s[84:85]
	v_cndmask_b32_e64 v38, v38, 0, s[86:87]
	v_cndmask_b32_e64 v39, v39, 0, s[88:89]
	v_cvt_pk_bf16_f32 v40, v48, v49
	v_cvt_pk_bf16_f32 v41, v50, v51
	v_cvt_pk_bf16_f32 v42, v180, v181
	v_cvt_pk_bf16_f32 v43, v182, v183
	v_cvt_pk_bf16_f32 v44, v188, v189
	v_cvt_pk_bf16_f32 v45, v190, v191
	v_cvt_pk_bf16_f32 v46, v36, v37
	v_cvt_pk_bf16_f32 v47, v38, v39
	s_waitcnt lgkmcnt(13)
	v_max_f32_e32 v0, v0, v0
	s_waitcnt lgkmcnt(12)
	v_mfma_f32_16x16x32_bf16 v[200:203], v[200:203], v[40:43], 0
	v_mfma_f32_16x16x32_bf16 v[204:207], v[204:207], v[40:43], 0
	v_mfma_f32_16x16x32_bf16 v[200:203], v[246:249], v[44:47], v[200:203]
	v_mfma_f32_16x16x32_bf16 v[204:207], v[216:219], v[44:47], v[204:207]
	v_pk_mul_f32 v[26:27], v[26:27], v[176:177] op_sel_hi:[1,0]
	v_pk_mul_f32 v[24:25], v[24:25], v[176:177] op_sel_hi:[1,0]
	v_mul_f32_e64 v18, v18, v176
	v_mul_f32_e64 v19, v19, v176
	v_pk_mul_f32 v[16:17], v[16:17], v[176:177] op_sel_hi:[1,0]
	v_mov_b32_e32 v250, v3
	s_waitcnt lgkmcnt(8)
	v_mfma_f32_16x16x32_bf16 v[24:27], v[192:195], v[52:55], v[24:27]
	s_waitcnt lgkmcnt(6)
	v_mfma_f32_16x16x32_bf16 v[16:19], v[196:199], v[52:55], v[16:19]
	s_waitcnt lgkmcnt(2)
	v_mfma_f32_16x16x32_bf16 v[24:27], v[234:237], v[184:187], v[24:27]
	s_waitcnt lgkmcnt(0)
	v_mfma_f32_16x16x32_bf16 v[16:19], v[242:245], v[184:187], v[16:19]
	v_pk_mul_f32 v[48:49], v[2:3], v[200:201] op_sel_hi:[0,1]
	v_pk_fma_f32 v[48:49], v[250:251], v[230:231], v[48:49] op_sel_hi:[0,1,1]
	v_pk_mul_f32 v[50:51], v[2:3], v[202:203] op_sel_hi:[0,1]
	v_pk_fma_f32 v[50:51], v[250:251], v[232:233], v[50:51] op_sel_hi:[0,1,1]
	v_mul_f32_e32 v2, v2, v204
	v_fma_f32 v2, v250, v238, v2
	ds_bpermute_b32 v2, v139, v2
	v_add3_u32 v168, s34, v115, v129
	v_cvt_pk_bf16_f32 v179, v24, 0
	v_cvt_pk_bf16_f32 v208, v25, 0
	v_cvt_pk_bf16_f32 v209, v26, 0
	v_cvt_pk_bf16_f32 v220, v27, 0
	ds_write_b16 v168, v179
	ds_write_b16 v168, v208 offset:144
	ds_write_b16 v168, v209 offset:288
	ds_write_b16 v168, v220 offset:432
	s_and_b64 vcc, exec, s[36:37]
	s_cbranch_vccnz .Lml_skip_ones
	v_add3_u32 v169, s34, v112, v115
	v_cvt_pk_bf16_f32 v179, v16, 0
	v_cvt_pk_bf16_f32 v208, v17, 0
	v_cvt_pk_bf16_f32 v209, v18, 0
	v_cvt_pk_bf16_f32 v220, v19, 0
	ds_write_b16 v169, v179 offset:4608
	ds_write_b16 v169, v208 offset:4752
	ds_write_b16 v169, v209 offset:4896
	ds_write_b16 v169, v220 offset:5040
.Lml_skip_ones:
	s_mul_i32 s0, s21, 0x2400
	s_waitcnt lgkmcnt(0)
	v_max_f32_e64 v2, |v2|, |v2|
	v_max_f32_e32 v0, v2, v0
	v_div_scale_f32 v2, s[22:23], v0, v0, 1.0
	v_rcp_f32_e32 v3, v2
	s_nop 0
	v_fma_f32 v36, -v2, v3, 1.0
	v_fmac_f32_e32 v3, v36, v3
	v_div_scale_f32 v36, vcc, 1.0, v0, 1.0
	v_mul_f32_e32 v37, v36, v3
	v_fma_f32 v38, -v2, v37, v36
	v_fmac_f32_e32 v37, v38, v3
	v_fma_f32 v2, -v2, v37, v36
	v_div_fmas_f32 v2, v2, v3, v37
	v_div_fixup_f32 v0, v2, v0, 1.0
	v_pk_mul_f32 v[2:3], v[48:49], v[0:1] op_sel_hi:[1,0]
	v_pk_mul_f32 v[36:37], v[50:51], v[0:1] op_sel_hi:[1,0]
	v_cvt_pk_bf16_f32 v2, v2, v3
	v_cvt_pk_bf16_f32 v3, v36, v37
	v_add_u32_e32 v0, s0, v101
	global_store_dwordx2 v[72:73], v[2:3], off
	s_waitcnt vmcnt(2)
	ds_write_b128 v0, v[28:31]
	s_waitcnt vmcnt(1)
	ds_write_b128 v0, v[32:35] offset:18432
	s_and_saveexec_b64 s[22:23], s[42:43]
	s_xor_b64 s[30:31], exec, s[22:23]
	s_cbranch_execnz .LBB0_263
	s_andn2_saveexec_b64 s[30:31], s[30:31]
	s_cbranch_execnz .LBB0_266
